# stack: xattn K stride 544 + static prio for waves 4-7 + first-unit loads ahead of the scale reduction; flat seam release; dattn V-load hoist
# baseline (speedup 1.0000x reference)
.LBB0_1947:
	v_readlane_b32 s4, v244, 47
	s_cmp_lt_i32 s4, 10
	s_cselect_b64 s[2:3], -1, 0
	s_and_b64 s[2:3], s[2:3], s[0:1]
	s_cmpk_lt_i32 s69, 0x600
	s_cselect_b64 s[0:1], -1, 0
	s_and_b64 s[0:1], s[2:3], s[0:1]
	s_andn2_b64 vcc, exec, s[0:1]
	v_readlane_b32 s5, v244, 48
	v_readlane_b32 s6, v244, 49
	v_readlane_b32 s7, v244, 50
	s_cbranch_vccnz .LBB0_1956
	v_and_b32_e32 v249, 63, v182
	v_readlane_b32 s4, v244, 6
	v_readlane_b32 s5, v244, 7
	v_readlane_b32 s6, v244, 39
	v_readlane_b32 s7, v244, 40
	v_readlane_b32 s8, v244, 41
	v_readlane_b32 s9, v244, 42
	v_lshlrev_b32_e32 v242, 2, v249
	s_nop 3
	global_load_dword v216, v242, s[6:7] offset:0
	global_load_dword v217, v242, s[6:7] offset:256
	global_load_dword v218, v242, s[6:7] offset:512
	global_load_dword v219, v242, s[6:7] offset:768
	global_load_dword v220, v242, s[8:9] offset:0
	global_load_dword v221, v242, s[8:9] offset:256
	global_load_dword v222, v242, s[8:9] offset:512
	global_load_dword v223, v242, s[8:9] offset:768
	v_and_b32_e32 v243, 15, v182
	v_bfe_u32 v245, v182, 4, 2
	v_lshl_or_b32 v246, s88, 4, v243
	v_lshlrev_b32_e32 v228, 11, v246
	v_lshl_add_u32 v238, v245, 3, v228
	v_lshl_add_u32 v228, v245, 4, v228
	v_add_u32_e32 v229, 0x40000, v228
	v_add_u32_e32 v239, 0x40000, v238
	v_lshlrev_b32_e32 v230, 4, v246
	v_mul_u32_u24_e32 v231, 528, v243
	v_lshl_add_u32 v232, v245, 3, v231
	v_mul_u32_u24_e32 v231, 544, v243
	v_lshl_add_u32 v231, v245, 4, v231
	v_lshrrev_b32_e32 v243, 5, v182
	v_and_b32_e32 v245, 31, v182
	v_lshlrev_b32_e32 v245, 4, v245
	v_lshl_add_u32 v224, v243, 11, v245
	v_mul_u32_u24_e32 v225, 5120, v243
	v_add_u32_e32 v225, v225, v245
	v_mul_u32_u24_e32 v226, 544, v243
	v_add_u32_e32 v226, v226, v245
	v_add_u32_e32 v227, 69632, v226
	v_and_b32_e32 v250, 3, v243
	v_bfe_u32 v242, v243, 2, 1
	v_lshl_or_b32 v250, v242, 4, v250
	v_bfe_u32 v242, v243, 3, 1
	v_lshl_or_b32 v250, v242, 2, v250
	v_mul_u32_u24_e32 v250, 528, v250
	v_add_u32_e32 v250, v250, v245
	v_add_u32_e32 v251, 67584, v250
	v_xor_b32_e32 v236, 16, v249
	v_lshlrev_b32_e32 v236, 2, v236
	v_xor_b32_e32 v237, 32, v249
	v_lshlrev_b32_e32 v237, 2, v237
	v_mov_b32_e32 v181, 0x358637bd
	s_and_b32 s0, s69, 31
	s_lshr_b32 s1, s69, 8
	s_lshl_b32 s1, s1, 5
	s_add_i32 s1, s1, s0
	s_mul_i32 s0, s1, 2731
	s_lshr_b32 s0, s0, 16
	s_mul_i32 s17, s0, 24
	s_sub_i32 s1, s1, s17
	s_bfe_u32 s17, s69, 0x30005
	s_mul_i32 s17, s17, 24
	s_add_i32 s1, s1, s17
	s_lshl_b32 s11, s1, 19
	s_lshl_b32 s12, s0, 9
	s_add_u32 s11, s11, s12
	s_add_u32 s12, s11, 0xf000000
	s_add_u32 s10, s4, s12
	s_addc_u32 s11, s5, 0
	s_lshl_b32 s12, s1, 12
	s_lshl_b32 s13, s0, 2
	s_add_u32 s12, s12, s13
	s_add_u32 s12, s12, 0x1fa60000
	s_add_u32 s12, s4, s12
	s_addc_u32 s13, s5, 0
	global_load_dwordx4 v[0:3], v228, s[10:11] offset:0
	global_load_dwordx4 v[4:7], v228, s[10:11] offset:64
	global_load_dwordx4 v[8:11], v228, s[10:11] offset:128
	global_load_dwordx4 v[12:15], v228, s[10:11] offset:192
	global_load_dwordx4 v[16:19], v228, s[10:11] offset:256
	global_load_dwordx4 v[20:23], v228, s[10:11] offset:320
	global_load_dwordx4 v[24:27], v228, s[10:11] offset:384
	global_load_dwordx4 v[28:31], v228, s[10:11] offset:448
	global_load_dwordx4 v[32:35], v229, s[10:11] offset:0
	global_load_dwordx4 v[36:39], v229, s[10:11] offset:64
	global_load_dwordx4 v[40:43], v229, s[10:11] offset:128
	global_load_dwordx4 v[44:47], v229, s[10:11] offset:192
	global_load_dwordx4 v[48:51], v229, s[10:11] offset:256
	global_load_dwordx4 v[52:55], v229, s[10:11] offset:320
	global_load_dwordx4 v[56:59], v229, s[10:11] offset:384
	global_load_dwordx4 v[60:63], v229, s[10:11] offset:448
	global_load_dword v247, v230, s[12:13]
	global_load_dword v248, v230, s[12:13] offset:2048
	s_lshr_b32 s10, s1, 5
	s_sub_i32 s11, s1, 64
	s_lshr_b32 s11, s11, 4
	s_add_i32 s11, s11, 2
	s_cmp_lt_u32 s1, 64
	s_cselect_b32 s10, s10, s11
	s_lshl_b32 s11, s10, 19
	s_lshl_b32 s12, s0, 9
	s_add_u32 s11, s11, s12
	s_add_u32 s11, s11, 0x15040000
	s_add_u32 s6, s4, s11
	s_addc_u32 s7, s5, 0
	global_load_dwordx4 v[184:187], v224, s[6:7]
	s_add_u32 s6, s6, 0x8000
	s_addc_u32 s7, s7, 0
	global_load_dwordx4 v[188:191], v224, s[6:7]
	s_add_u32 s6, s6, 0x8000
	s_addc_u32 s7, s7, 0
	global_load_dwordx4 v[192:195], v224, s[6:7]
	s_add_u32 s6, s6, 0x8000
	s_addc_u32 s7, s7, 0
	global_load_dwordx4 v[196:199], v224, s[6:7]
	s_add_u32 s6, s6, 0x8000
	s_addc_u32 s7, s7, 0
	global_load_dwordx4 v[200:203], v224, s[6:7]
	s_add_u32 s6, s6, 0x8000
	s_addc_u32 s7, s7, 0
	global_load_dwordx4 v[204:207], v224, s[6:7]
	s_add_u32 s6, s6, 0x8000
	s_addc_u32 s7, s7, 0
	global_load_dwordx4 v[208:211], v224, s[6:7]
	s_add_u32 s6, s6, 0x8000
	s_addc_u32 s7, s7, 0
	global_load_dwordx4 v[212:215], v224, s[6:7]
	s_waitcnt vmcnt(26)
	v_mul_f32_e32 v216, v216, v220
	v_mul_f32_e32 v217, v217, v221
	v_mul_f32_e32 v218, v218, v222
	v_mul_f32_e32 v219, v219, v223
	v_max_f32_e64 v216, |v216|, |v217|
	v_max_f32_e64 v218, |v218|, |v219|
	v_max_f32_e32 v216, v216, v218
	v_xor_b32_e32 v242, 1, v249
	v_lshlrev_b32_e32 v242, 2, v242
	ds_bpermute_b32 v243, v242, v216
	s_waitcnt lgkmcnt(0)
	v_max_f32_e32 v216, v216, v243
	v_xor_b32_e32 v242, 2, v249
	v_lshlrev_b32_e32 v242, 2, v242
	ds_bpermute_b32 v243, v242, v216
	s_waitcnt lgkmcnt(0)
	v_max_f32_e32 v216, v216, v243
	v_xor_b32_e32 v242, 4, v249
	v_lshlrev_b32_e32 v242, 2, v242
	ds_bpermute_b32 v243, v242, v216
	s_waitcnt lgkmcnt(0)
	v_max_f32_e32 v216, v216, v243
	v_xor_b32_e32 v242, 8, v249
	v_lshlrev_b32_e32 v242, 2, v242
	ds_bpermute_b32 v243, v242, v216
	s_waitcnt lgkmcnt(0)
	v_max_f32_e32 v216, v216, v243
	v_xor_b32_e32 v242, 16, v249
	v_lshlrev_b32_e32 v242, 2, v242
	ds_bpermute_b32 v243, v242, v216
	s_waitcnt lgkmcnt(0)
	v_max_f32_e32 v216, v216, v243
	v_xor_b32_e32 v242, 32, v249
	v_lshlrev_b32_e32 v242, 2, v242
	ds_bpermute_b32 v243, v242, v216
	s_waitcnt lgkmcnt(0)
	v_max_f32_e32 v216, v216, v243
	v_mul_f32_e32 v180, 0x41b8aa3b, v216
	s_cmp_ge_u32 s88, 4
	s_cbranch_scc0 .Lxa_noprio
	s_setprio 1
